# P0 x->bf16 loop unrolled 4x (8 loads in flight per lane, store acks off the wait path) + attention DMA address diet
# speedup vs baseline: 1.0004x; 1.0004x over previous
.LBB0_51:
	s_mov_b32 s3, 0
	s_lshl_b64 s[10:11], s[2:3], 9
	s_and_b32 s3, s25, 0xffffffc0
	s_ashr_i32 s12, s3, 31
	s_add_u32 s10, s10, s3
	s_addc_u32 s11, s11, s12
	v_ashrrev_i32_e32 v3, 31, v2
	v_lshl_add_u64 v[2:3], s[10:11], 0, v[2:3]
	s_mov_b64 s[10:11], 0x800000
	v_cmp_gt_u64_e32 vcc, s[10:11], v[2:3]
	s_and_saveexec_b64 s[10:11], vcc
	s_cbranch_execz .LBB0_54
	v_lshlrev_b64 v[6:7], 5, v[2:3]
	s_ashr_i32 s25, s24, 31
	v_lshl_add_u64 v[6:7], s[8:9], 0, v[6:7]
	s_lshl_b64 s[12:13], s[24:25], 9
	v_lshl_add_u64 v[4:5], v[2:3], 4, s[6:7]
	s_lshl_b64 s[6:7], s[24:25], 13
	v_lshl_add_u64 v[6:7], v[6:7], 0, 16
	s_lshl_b64 s[8:9], s[24:25], 14
	s_mov_b64 s[14:15], 0
	s_mov_b64 s[28:29], 0x7fffff
	v_readfirstlane_b32 s34, v2
	s_mul_i32 s35, s12, 3
	s_add_u32 s35, s35, 63
	s_lshl_b32 s36, s12, 2
	s_mov_b32 s40, s36
	s_mov_b32 s41, 0
.Lxq_top:
	s_add_u32 s37, s34, s35
	s_cmp_lt_u32 s37, 0x800000
	s_cbranch_scc0 .Lxq_done
	global_load_dwordx4 v[16:19], v[6:7], off offset:-16
	global_load_dwordx4 v[20:23], v[6:7], off
	v_lshl_add_u64 v[48:49], v[6:7], 0, s[8:9]
	global_load_dwordx4 v[24:27], v[48:49], off offset:-16
	global_load_dwordx4 v[28:31], v[48:49], off
	v_lshl_add_u64 v[48:49], v[48:49], 0, s[8:9]
	global_load_dwordx4 v[32:35], v[48:49], off offset:-16
	global_load_dwordx4 v[36:39], v[48:49], off
	v_lshl_add_u64 v[48:49], v[48:49], 0, s[8:9]
	global_load_dwordx4 v[40:43], v[48:49], off offset:-16
	global_load_dwordx4 v[44:47], v[48:49], off
	v_lshl_add_u64 v[6:7], v[48:49], 0, s[8:9]
	v_lshl_add_u64 v[2:3], v[2:3], 0, s[40:41]
	s_add_u32 s34, s34, s36
	s_waitcnt vmcnt(6)
	v_add_u32_e32 v16, 0x10000, v16
	v_add_u32_e32 v17, 0x10000, v17
	v_add_u32_e32 v18, 0x10000, v18
	v_add_u32_e32 v19, 0x10000, v19
	v_add_u32_e32 v20, 0x10000, v20
	v_add_u32_e32 v21, 0x10000, v21
	v_add_u32_e32 v22, 0x10000, v22
	v_add_u32_e32 v23, 0x10000, v23
	v_and_b32_e32 v16, 0xfffe0000, v16
	v_and_b32_e32 v17, 0xfffe0000, v17
	v_and_b32_e32 v18, 0xfffe0000, v18
	v_and_b32_e32 v19, 0xfffe0000, v19
	v_and_b32_e32 v20, 0xfffe0000, v20
	v_and_b32_e32 v21, 0xfffe0000, v21
	v_and_b32_e32 v22, 0xfffe0000, v22
	v_and_b32_e32 v23, 0xfffe0000, v23
	v_cvt_pk_bf16_f32 v16, v16, v17
	v_cvt_pk_bf16_f32 v17, v18, v19
	v_cvt_pk_bf16_f32 v18, v20, v21
	v_cvt_pk_bf16_f32 v19, v22, v23
	global_store_dwordx4 v[4:5], v[16:19], off
	v_lshl_add_u64 v[4:5], v[4:5], 0, s[6:7]
	s_waitcnt vmcnt(5)
	v_add_u32_e32 v24, 0x10000, v24
	v_add_u32_e32 v25, 0x10000, v25
	v_add_u32_e32 v26, 0x10000, v26
	v_add_u32_e32 v27, 0x10000, v27
	v_add_u32_e32 v28, 0x10000, v28
	v_add_u32_e32 v29, 0x10000, v29
	v_add_u32_e32 v30, 0x10000, v30
	v_add_u32_e32 v31, 0x10000, v31
	v_and_b32_e32 v24, 0xfffe0000, v24
	v_and_b32_e32 v25, 0xfffe0000, v25
	v_and_b32_e32 v26, 0xfffe0000, v26
	v_and_b32_e32 v27, 0xfffe0000, v27
	v_and_b32_e32 v28, 0xfffe0000, v28
	v_and_b32_e32 v29, 0xfffe0000, v29
	v_and_b32_e32 v30, 0xfffe0000, v30
	v_and_b32_e32 v31, 0xfffe0000, v31
	v_cvt_pk_bf16_f32 v24, v24, v25
	v_cvt_pk_bf16_f32 v25, v26, v27
	v_cvt_pk_bf16_f32 v26, v28, v29
	v_cvt_pk_bf16_f32 v27, v30, v31
	global_store_dwordx4 v[4:5], v[24:27], off
	v_lshl_add_u64 v[4:5], v[4:5], 0, s[6:7]
	s_waitcnt vmcnt(4)
	v_add_u32_e32 v32, 0x10000, v32
	v_add_u32_e32 v33, 0x10000, v33
	v_add_u32_e32 v34, 0x10000, v34
	v_add_u32_e32 v35, 0x10000, v35
	v_add_u32_e32 v36, 0x10000, v36
	v_add_u32_e32 v37, 0x10000, v37
	v_add_u32_e32 v38, 0x10000, v38
	v_add_u32_e32 v39, 0x10000, v39
	v_and_b32_e32 v32, 0xfffe0000, v32
	v_and_b32_e32 v33, 0xfffe0000, v33
	v_and_b32_e32 v34, 0xfffe0000, v34
	v_and_b32_e32 v35, 0xfffe0000, v35
	v_and_b32_e32 v36, 0xfffe0000, v36
	v_and_b32_e32 v37, 0xfffe0000, v37
	v_and_b32_e32 v38, 0xfffe0000, v38
	v_and_b32_e32 v39, 0xfffe0000, v39
	v_cvt_pk_bf16_f32 v32, v32, v33
	v_cvt_pk_bf16_f32 v33, v34, v35
	v_cvt_pk_bf16_f32 v34, v36, v37
	v_cvt_pk_bf16_f32 v35, v38, v39
	global_store_dwordx4 v[4:5], v[32:35], off
	v_lshl_add_u64 v[4:5], v[4:5], 0, s[6:7]
	s_waitcnt vmcnt(3)
	v_add_u32_e32 v40, 0x10000, v40
	v_add_u32_e32 v41, 0x10000, v41
	v_add_u32_e32 v42, 0x10000, v42
	v_add_u32_e32 v43, 0x10000, v43
	v_add_u32_e32 v44, 0x10000, v44
	v_add_u32_e32 v45, 0x10000, v45
	v_add_u32_e32 v46, 0x10000, v46
	v_add_u32_e32 v47, 0x10000, v47
	v_and_b32_e32 v40, 0xfffe0000, v40
	v_and_b32_e32 v41, 0xfffe0000, v41
	v_and_b32_e32 v42, 0xfffe0000, v42
	v_and_b32_e32 v43, 0xfffe0000, v43
	v_and_b32_e32 v44, 0xfffe0000, v44
	v_and_b32_e32 v45, 0xfffe0000, v45
	v_and_b32_e32 v46, 0xfffe0000, v46
	v_and_b32_e32 v47, 0xfffe0000, v47
	v_cvt_pk_bf16_f32 v40, v40, v41
	v_cvt_pk_bf16_f32 v41, v42, v43
	v_cvt_pk_bf16_f32 v42, v44, v45
	v_cvt_pk_bf16_f32 v43, v46, v47
	global_store_dwordx4 v[4:5], v[40:43], off
	v_lshl_add_u64 v[4:5], v[4:5], 0, s[6:7]
	s_branch .Lxq_top
.Lxq_done:
	v_cmp_ge_u64_e32 vcc, s[28:29], v[2:3]
	s_and_b64 exec, exec, vcc
	s_cbranch_execz .LBB0_54
